# ret_out: one static s_setprio 1 for waves 4-7 over the retention-output items (reset at the conv entry)
# speedup vs baseline: 1.0003x; 1.0003x over previous
.Lp6_retout_entry:
	v_readfirstlane_b32 s99, v160
	s_nop 3
	s_lshr_b32 s99, s99, 8
	s_cmp_eq_u32 s99, 0
	s_cbranch_scc1 .Lro_prio_done
	s_setprio 1

.LBB0_905:
	s_setprio 0
	s_cmp_eq_u32 s100, 2
	s_cbranch_scc1 .LBB0_945
	s_cmp_lt_i32 s92, 6
	s_cselect_b64 s[4:5], -1, 0
	s_cmpk_lt_i32 s20, 0x200
	s_cselect_b64 s[0:1], -1, 0
	s_and_b64 s[4:5], s[4:5], s[0:1]
	s_and_b64 s[2:3], s[4:5], s[2:3]
	s_andn2_b64 vcc, exec, s[2:3]
	s_cbranch_vccnz .LBB0_945
	s_waitcnt vmcnt(0)
	v_or_b32_e32 v1, 0x400, v160
	v_sub_u32_e32 v4, 0x1010, v1
	v_or_b32_e32 v1, 0x800, v160
	v_sub_u32_e32 v8, 0x1010, v1
	v_or_b32_e32 v1, 0xc00, v160
	v_sub_u32_e32 v12, 0x1010, v1
	v_sub_u32_e32 v1, 0x210, v160
	v_sub_u32_e32 v3, 0, v1
	s_movk_i32 s2, 0x211
	v_max_i32_e32 v162, v1, v3
	v_mov_b32_e32 v1, 0x800000
	v_cmp_gt_u32_e32 vcc, s2, v160
	v_or_b32_e32 v3, 0x1000, v160
	s_movk_i32 s2, 0x1011
	v_cndmask_b32_e64 v164, v1, 0, vcc
	v_cmp_gt_u32_e32 vcc, s2, v3
	v_sub_u32_e32 v5, 0x1010, v3
	s_movk_i32 s10, 0x2018
	v_cndmask_b32_e64 v168, v1, 0, vcc
	v_or_b32_e32 v1, 0x2000, v160
	v_sub_u32_e32 v7, 0, v5
	v_cmp_gt_u32_e64 s[10:11], s10, v1
	v_lshrrev_b32_e32 v1, 5, v160
	v_max_i32_e32 v166, v5, v7
	v_and_b32_e32 v5, 31, v160
	v_and_b32_e32 v9, 30, v1
	v_mul_i32_i24_e32 v11, 0xffffff00, v9
	v_lshlrev_b32_e32 v170, 3, v5
	v_sub_u32_e32 v3, 0x1010, v160
	v_bfe_u32 v7, v160, 5, 1
	v_sub_u32_e32 v11, v11, v170
	v_mov_b32_e32 v0, 0
	v_min_u32_e32 v18, 0xfff, v3
	v_bfe_u32 v3, v160, 5, 3
	v_lshlrev_b32_e32 v13, 4, v7
	v_lshlrev_b32_e32 v11, 1, v11
	s_movk_i32 s12, 0x410
	v_lshlrev_b32_e32 v20, 13, v3
	v_mov_b32_e32 v21, v0
	v_add3_u32 v201, 0, v11, v13
	v_and_b32_e32 v11, 7, v160
	s_add_u32 s42, s22, 0x1cb6000
	v_mad_u32_u24 v196, v5, s12, v13
	v_lshl_add_u64 v[20:21], s[22:23], 0, v[20:21]
	s_mov_b64 s[12:13], 0x194bc000
	v_lshlrev_b32_e32 v13, 9, v160
	v_lshlrev_b32_e32 v24, 1, v11
	v_mov_b32_e32 v25, v0
	s_addc_u32 s43, s23, 0
	v_lshl_add_u64 v[174:175], v[20:21], 0, s[12:13]
	s_movk_i32 s26, 0x2080
	v_and_b32_e32 v20, 0x3000, v13
	v_lshlrev_b32_e32 v22, 5, v7
	v_lshl_add_u64 v[24:25], s[22:23], 0, v[24:25]
	s_mov_b64 s[28:29], 0x1b4bc000
	v_mov_b32_e32 v7, 0x100
	s_add_u32 s44, s22, 0x2cb6000
	v_sub_u32_e32 v2, 0xe10, v160
	v_sub_u32_e32 v6, 0xa10, v160
	v_sub_u32_e32 v10, 0x610, v160
	s_movk_i32 s8, 0x20f
	v_min_u32_e32 v14, 0x20f, v160
	v_min_u32_e32 v16, 15, v160
	s_movk_i32 s6, 0x218
	v_cmp_lt_u32_e64 s[12:13], 1, v5
	v_cmp_ne_u32_e64 s[14:15], 0, v5
	s_movk_i32 s16, 0xff
	v_mul_u32_u24_e32 v197, 0x2080, v3
	v_mad_u32_u24 v3, v3, s26, 0
	v_lshlrev_b32_e32 v198, 4, v5
	v_mad_u32_u24 v5, v1, s26, 0
	v_lshl_add_u64 v[176:177], v[24:25], 0, s[28:29]
	v_lshlrev_b32_e32 v24, 8, v9
	v_or_b32_e32 v26, 0x4000, v20
	v_lshl_or_b32 v28, v1, 8, v7
	s_addc_u32 s45, s23, 0
	s_mov_b32 s27, 0
	s_mov_b32 s46, 0x800000
	v_mov_b32_e32 v165, v0
	v_mov_b32_e32 v163, v0
	s_movk_i32 s47, 0x1000
	v_mov_b32_e32 v169, v0
	v_mov_b32_e32 v167, v0
	v_mov_b32_e32 v161, v0
	v_cmp_lt_u32_e64 s[2:3], 15, v160
	v_cmp_gt_u32_e64 s[4:5], 17, v160
	v_lshl_add_u32 v171, v160, 1, 0
	v_cmp_gt_u32_e64 s[6:7], s6, v160
	v_cmp_lt_u32_e64 s[8:9], s8, v160
	v_add_u32_e32 v172, -16, v170
	v_mov_b32_e32 v173, v0
	v_cmp_lt_u32_e64 s[16:17], s16, v160
	v_mul_u32_u24_e32 v199, 0x2080, v1
	v_add_u32_e32 v200, 0x3f0, v170
	v_lshlrev_b32_e32 v202, 2, v2
	v_lshlrev_b32_e32 v203, 2, v4
	v_lshlrev_b32_e32 v204, 2, v6
	v_lshlrev_b32_e32 v205, 2, v8
	v_lshlrev_b32_e32 v206, 2, v10
	v_lshlrev_b32_e32 v207, 2, v12
	s_mov_b32 s48, 0x801000
	s_mov_b32 s49, 0x802000
	v_lshlrev_b32_e32 v178, 2, v16
	v_lshlrev_b32_e32 v208, 2, v18
	s_movk_i32 s52, 0x7fff
	v_lshlrev_b32_e32 v180, 2, v14
	v_add_u32_e32 v209, v3, v198
	s_mov_b32 s53, 0x1000706
	v_add_u32_e32 v210, v5, v198
	s_movk_i32 s54, 0xff8
	s_movk_i32 s55, 0xf00
	s_movk_i32 s56, 0xef8
	v_lshlrev_b32_e32 v182, 1, v24
	v_lshlrev_b32_e32 v184, 1, v20
	v_lshlrev_b32_e32 v186, 1, v22
	v_lshlrev_b32_e32 v188, 1, v26
	v_lshlrev_b32_e32 v190, 1, v28
	v_mov_b32_e32 v179, v0
	s_mov_b32 s38, s20
	s_branch .LBB0_908
